# D tile loop: accumulators rescaled only when a running max grows by more than 8 log2 units (reference kept otherwise; exact softmax)
# speedup vs baseline: 1.0039x; 1.0039x over previous
; #define LAS __attribute__((address_space(3)))
; DI float fexp2(float x) { return __builtin_amdgcn_exp2f(x); }
; DI float half_max(float v) { auto rr = __builtin_amdgcn_permlane32_swap(__float_as_uint(v), __float_as_uint(v), false, false); return fmaxf(__uint_as_float(rr[0]), __uint_as_float(rr[1])); }
; DI s16x4 vtr(LAS const unsigned char* p) { return __builtin_bit_cast(s16x4, __builtin_amdgcn_ds_read_tr16_b64_v4i16((LAS v4i16_t*)p)); }
; #define MFMA32(a, b, c) __builtin_amdgcn_mfma_f32_32x32x16_bf16((a), (b), (c), 0, 0, 0)
; template <bool MASKED>
; DI void attn_tile_sw(int MODE, LAS const unsigned char* kst, LAS const unsigned char* vst, const bf16x8 (&qf)[4], float bstep, float ca, int lane, f32x16& o0, f32x16& o1, float& m, float& l) {
;     ...
;         for (int st = 0; st < 4; ++st) kf[st] = *(LAS const bf16x8*)(kst + qq * 128 + (((2 * st + hh) ^ (qq & 7)) << 4));
; #pragma unroll
;         for (int st = 0; st < 4; ++st) s = MFMA32(kf[st], qf[st], s); }
;     const int q4 = (lane & 15) >> 2, p = lane & 3, blk = (lane >> 4) & 1, x = 4 * hh + q4;
;     LAS const unsigned char* vb = vst + x * 128 + 8 * (p & 1);
;     const int ch0 = ((2 * blk + (p >> 1)) ^ x) << 4, ch1 = ((4 + 2 * blk + (p >> 1)) ^ x) << 4;
;     const s16x4 va0 = vtr(vb + ch0), va1 = vtr(vb + 8 * 128 + ch0), vb0 = vtr(vb + ch1), vb1 = vtr(vb + 8 * 128 + ch1);
;     const s16x4 vc0 = vtr(vb + 16 * 128 + ch0), vc1 = vtr(vb + 24 * 128 + ch0), vd0 = vtr(vb + 16 * 128 + ch1), vd1 = vtr(vb + 24 * 128 + ch1);
;     if (MASKED) { const int dq = (MODE == 1) ? (qq - 4 * hh) : (4 * hh - qq);
; #pragma unroll
;         for (int r = 0; r < 16; ++r) { const int kq = (r & 3) + 8 * (r >> 2); s[r] = (((MODE == 1) ? kq : -kq) < dq) ? NEG : s[r]; } }
;     float tmax = vmax3(s[0], s[1], s[2]);
;     tmax = vmax3(tmax, s[3], s[4]); tmax = vmax3(tmax, s[5], s[6]); tmax = vmax3(tmax, s[7], s[8]); tmax = vmax3(tmax, s[9], s[10]);
;     tmax = vmax3(tmax, s[11], s[12]); tmax = vmax3(tmax, s[13], s[14]); tmax = fmaxf(tmax, s[15]);
;     tmax = half_max(tmax);
;     const float mn = fmaxf(m, tmax + ca), mrel = mn - ca;
;     if (__builtin_amdgcn_ballot_w64(mn > m) != 0ull) { const float alpha = fexp2(m - mn); l *= alpha;
; #pragma unroll
;         for (int i = 0; i < 16; ++i) { o0[i] *= alpha; o1[i] *= alpha; } }
;     m = mn;
.Ldil_qk_join:
	ds_read_b128 v[4:7], v237
	ds_read_b128 v[12:15], v238
	s_waitcnt lgkmcnt(2)
	v_mfma_f32_32x32x16_bf16 v[98:113], v[8:11], v[170:173], v[98:113]
	ds_read_b64_tr_b16 v[178:179], v239 offset:4096
	ds_read_b64_tr_b16 v[180:181], v239 offset:5120
	ds_read_b64_tr_b16 v[8:9], v239 offset:6144
	ds_read_b64_tr_b16 v[10:11], v239 offset:7168
	s_waitcnt lgkmcnt(5)
	v_mfma_f32_32x32x16_bf16 v[98:113], v[4:7], v[166:169], v[98:113]
	s_waitcnt lgkmcnt(4)
	v_mfma_f32_32x32x16_bf16 v[98:113], v[12:15], v[162:165], v[98:113]
	ds_read_b64_tr_b16 v[12:13], v240 offset:4096
	ds_read_b64_tr_b16 v[14:15], v240 offset:5120
	ds_read_b64_tr_b16 v[4:5], v240 offset:6144
	ds_read_b64_tr_b16 v[6:7], v240 offset:7168
	v_cvt_f32_i32_e32 v3, s51
	s_cmp_le_i32 s31, s47
	s_cselect_b64 s[26:27], -1, 0
	v_mul_f32_e64 v3, -v199, v3
	s_add_i32 s51, s51, 32
	s_add_i32 s31, s31, -1
	s_nop 1
	v_max3_f32 v17, v98, v99, v100
	v_max3_f32 v16, v101, v102, v103
	v_max3_f32 v17, v17, v104, v105
	v_max3_f32 v16, v16, v106, v107
	v_max3_f32 v17, v17, v108, v109
	v_max3_f32 v16, v16, v110, v111
	v_max3_f32 v17, v17, v112, v113
	v_max_f32_e32 v17, v17, v16
	v_mov_b32_e32 v16, v17
	s_nop 1
	v_permlane32_swap_b32_e32 v17, v16
	v_max_f32_e32 v17, v17, v16
	v_add_f32_e32 v17, v3, v17
	v_max_f32_e32 v17, v198, v17
	s_cmp_eq_u32 s31, 3
	s_cbranch_scc1 .Ldil_norescale
	v_sub_f32_e32 v16, v17, v198
	v_cmp_lt_f32_e32 vcc, 0x41000000, v16
	s_cbranch_vccnz .Ldil_rescale
	v_mov_b32_e32 v17, v198
	s_branch .Ldil_norescale
.Ldil_rescale:
	v_sub_f32_e32 v16, v198, v17
	v_exp_f32_e32 v16, v16
	s_nop 0
	v_mul_f32_e32 v185, v185, v16
	v_pk_mul_f32 v[66:67], v[66:67], v[16:17] op_sel_hi:[1,0]
	v_pk_mul_f32 v[68:69], v[68:69], v[16:17] op_sel_hi:[1,0]
	v_pk_mul_f32 v[70:71], v[70:71], v[16:17] op_sel_hi:[1,0]
	v_pk_mul_f32 v[72:73], v[72:73], v[16:17] op_sel_hi:[1,0]
	v_pk_mul_f32 v[74:75], v[74:75], v[16:17] op_sel_hi:[1,0]
	v_pk_mul_f32 v[76:77], v[76:77], v[16:17] op_sel_hi:[1,0]
	v_pk_mul_f32 v[78:79], v[78:79], v[16:17] op_sel_hi:[1,0]
	v_pk_mul_f32 v[80:81], v[80:81], v[16:17] op_sel_hi:[1,0]
	v_pk_mul_f32 v[82:83], v[82:83], v[16:17] op_sel_hi:[1,0]
	v_pk_mul_f32 v[84:85], v[84:85], v[16:17] op_sel_hi:[1,0]
	v_pk_mul_f32 v[86:87], v[86:87], v[16:17] op_sel_hi:[1,0]
	v_pk_mul_f32 v[88:89], v[88:89], v[16:17] op_sel_hi:[1,0]
	v_pk_mul_f32 v[90:91], v[90:91], v[16:17] op_sel_hi:[1,0]
	v_pk_mul_f32 v[92:93], v[92:93], v[16:17] op_sel_hi:[1,0]
	v_pk_mul_f32 v[94:95], v[94:95], v[16:17] op_sel_hi:[1,0]
	v_pk_mul_f32 v[96:97], v[96:97], v[16:17] op_sel_hi:[1,0]
